# phase_out epilogue: residual x / ple_norm_g loads issued in one group per 16-row block (were 8 serialized round trips each draining the stores)
# speedup vs baseline: 1.0027x; 1.0027x over previous
; DI unsigned pk2(float a, float b) { f32x2 v = {a, b}; bfv2 r = __builtin_convertvector(v, bfv2); return __builtin_bit_cast(unsigned, r); }
; DI void phase_out(const Params& p, int l, char* lds) {
;     ...
;     for (int mi = 0; mi < 4; ++mi) {
;       const int R = mt * 128 + wm * 64 + mi * 16 + l15;
;       const float* xr = x_row(p, l, R);
;       const float* g2 = p.ple_norm_g + l * DM;
;       bf16_t* xb = p.o_r + (size_t)R * DM;
;       float sq = 0.f;
; #pragma unroll
;       for (int ni = 0; ni < 4; ++ni) {
;         const int c = nt * 128 + wn * 64 + ni * 16 + quad * 4;
;         const f32x4 xv = *(const f32x4*)(xr + c);
;         const f32x4 x1 = xv + acc[mi][ni];
;         *(f32x4*)(p.out + (size_t)R * DM + c) = x1;
;         const f32x4 gv = *(const f32x4*)(g2 + c);
;         u32x2 o; o[0] = pk2(x1[0] * gv[0], x1[1] * gv[1]); o[1] = pk2(x1[2] * gv[2], x1[3] * gv[3]);
;         *(u32x2*)(xb + c) = o;
;         sq += x1[0] * x1[0] + x1[1] * x1[1] + x1[2] * x1[2] + x1[3] * x1[3];
;       }
;       sq += __shfl_xor(sq, 16); sq += __shfl_xor(sq, 32);
;       if (quad == 0) atomicAdd(p.ss2 + R, sq);
;     }
.LBB0_795:
	v_lshl_or_b32 v70, s24, 7, v83
	v_lshlrev_b64 v[72:73], 12, v[72:73]
	v_ashrrev_i32_e32 v71, 31, v70
	v_lshl_add_u64 v[66:67], v[66:67], 0, v[72:73]
	v_lshlrev_b64 v[72:73], 2, v[70:71]
	v_lshl_add_u64 v[78:79], v[66:67], 0, v[72:73]
	v_readlane_b32 s68, v251, 49
	v_lshlrev_b64 v[66:67], 12, v[68:69]
	v_readlane_b32 s70, v251, 51
	v_readlane_b32 s71, v251, 52
	v_lshlrev_b64 v[80:81], 11, v[68:69]
	v_lshl_add_u64 v[80:81], s[52:53], 0, v[80:81]
	v_lshl_add_u64 v[66:67], s[70:71], 0, v[66:67]
	v_lshl_add_u64 v[84:85], v[66:67], 0, v[72:73]
	v_lshl_add_u64 v[66:67], s[22:23], 0, v[72:73]
	v_lshl_add_u64 v[86:87], v[70:71], 1, v[80:81]
	v_add_u32_e32 v0, 64, v137
	v_cmp_lt_i32_e32 vcc, v136, v0
	v_readlane_b32 s69, v251, 50
	v_readlane_b32 s72, v251, 53
	v_readlane_b32 s73, v251, 54
	v_readlane_b32 s74, v251, 55
	v_readlane_b32 s75, v251, 56
	v_readlane_b32 s76, v251, 57
	v_readlane_b32 s77, v251, 58
	v_readlane_b32 s78, v251, 59
	v_readlane_b32 s79, v251, 60
	v_readlane_b32 s80, v251, 61
	v_readlane_b32 s81, v251, 62
	v_readlane_b32 s82, v251, 63
	v_readlane_b32 s83, v252, 0
	global_load_dwordx4 v[112:115], v[78:79], off
	global_load_dwordx4 v[116:119], v[66:67], off
	global_load_dwordx4 v[120:123], v[78:79], off offset:64
	global_load_dwordx4 v[214:217], v[66:67], off offset:64
	global_load_dwordx4 v[222:225], v[78:79], off offset:128
	global_load_dwordx4 v[226:229], v[66:67], off offset:128
	s_waitcnt vmcnt(0)
	v_pk_add_f32 v[64:65], v[64:65], v[114:115]
	v_pk_add_f32 v[62:63], v[62:63], v[112:113]
	global_store_dwordx4 v[84:85], v[62:65], off
	v_pk_mul_f32 v[76:77], v[64:65], v[118:119]
	v_pk_mul_f32 v[74:75], v[62:63], v[116:117]
	s_nop 0
	v_cvt_pk_bf16_f32 v74, v74, v75
	v_cvt_pk_bf16_f32 v75, v76, v77
	global_store_dwordx2 v[86:87], v[74:75], off
	v_pk_add_f32 v[60:61], v[60:61], v[122:123]
	v_pk_add_f32 v[58:59], v[58:59], v[120:121]
	global_store_dwordx4 v[84:85], v[58:61], off offset:64
	v_pk_mul_f32 v[76:77], v[60:61], v[216:217]
	v_pk_mul_f32 v[74:75], v[58:59], v[214:215]
	s_nop 0
	v_cvt_pk_bf16_f32 v74, v74, v75
	v_cvt_pk_bf16_f32 v75, v76, v77
	global_store_dwordx2 v[86:87], v[74:75], off offset:32
	v_pk_add_f32 v[76:77], v[56:57], v[224:225]
	v_pk_add_f32 v[74:75], v[54:55], v[222:223]
	global_store_dwordx4 v[84:85], v[74:77], off offset:128
	v_pk_mul_f32 v[56:57], v[76:77], v[228:229]
	v_pk_mul_f32 v[54:55], v[74:75], v[226:227]
	s_nop 0
	v_cvt_pk_bf16_f32 v54, v54, v55
	v_cvt_pk_bf16_f32 v55, v56, v57
	global_store_dwordx2 v[86:87], v[54:55], off offset:64
	global_load_dwordx4 v[54:57], v[78:79], off offset:192
	s_waitcnt vmcnt(0)
	v_pk_add_f32 v[80:81], v[52:53], v[56:57]
	v_pk_add_f32 v[78:79], v[50:51], v[54:55]
	global_store_dwordx4 v[84:85], v[78:81], off offset:192
	global_load_dwordx4 v[52:55], v[66:67], off offset:192
	v_cndmask_b32_e32 v50, v218, v136, vcc
	v_lshlrev_b32_e32 v56, 2, v50
	v_mul_f32_e32 v50, v63, v63
	v_mul_f32_e32 v51, v59, v59
	v_fmac_f32_e32 v50, v62, v62
	v_fmac_f32_e32 v51, v58, v58
	v_fmac_f32_e32 v50, v64, v64
	v_fmac_f32_e32 v51, v60, v60
	v_fmac_f32_e32 v50, v65, v65
	v_fmac_f32_e32 v51, v61, v61
	v_add_f32_e32 v50, v50, v51
	v_mul_f32_e32 v51, v75, v75
	v_fmac_f32_e32 v51, v74, v74
	v_fmac_f32_e32 v51, v76, v76
	v_fmac_f32_e32 v51, v77, v77
	v_add_f32_e32 v50, v50, v51
	v_mul_f32_e32 v51, v79, v79
	v_fmac_f32_e32 v51, v78, v78
	v_fmac_f32_e32 v51, v80, v80
	v_fmac_f32_e32 v51, v81, v81
	v_add_f32_e32 v50, v50, v51
	ds_bpermute_b32 v51, v56, v50
	v_cmp_lt_i32_e32 vcc, v138, v0
	s_waitcnt vmcnt(0)
	v_pk_mul_f32 v[54:55], v[80:81], v[54:55]
	v_cndmask_b32_e32 v0, v218, v138, vcc
	v_lshlrev_b32_e32 v57, 2, v0
	s_waitcnt lgkmcnt(0)
	v_add_f32_e32 v0, v50, v51
	ds_bpermute_b32 v50, v57, v0
	v_pk_mul_f32 v[52:53], v[78:79], v[52:53]
	s_nop 0
	v_cvt_pk_bf16_f32 v52, v52, v53
	v_cvt_pk_bf16_f32 v53, v54, v55
	global_store_dwordx2 v[86:87], v[52:53], off offset:96
	s_and_saveexec_b64 s[24:25], s[0:1]
	s_cbranch_execz .LBB0_797
	v_readlane_b32 s40, v254, 52
	v_readlane_b32 s42, v254, 54
	v_readlane_b32 s43, v254, 55
	s_waitcnt lgkmcnt(0)
	v_add_f32_e32 v0, v0, v50
	v_readlane_b32 s41, v254, 53
	v_lshl_add_u64 v[52:53], v[68:69], 2, s[42:43]
	global_atomic_add_f32 v[52:53], v0, off
	v_readlane_b32 s44, v254, 56
	v_readlane_b32 s45, v254, 57
	v_readlane_b32 s46, v254, 58
	v_readlane_b32 s47, v254, 59

; DI unsigned pk2(float a, float b) { f32x2 v = {a, b}; bfv2 r = __builtin_convertvector(v, bfv2); return __builtin_bit_cast(unsigned, r); }
; DI void phase_out(const Params& p, int l, char* lds) {
;     ...
;     for (int mi = 0; mi < 4; ++mi) {
;       const int R = mt * 128 + wm * 64 + mi * 16 + l15;
;       const float* xr = x_row(p, l, R);
;       const float* g2 = p.ple_norm_g + l * DM;
;       bf16_t* xb = p.o_r + (size_t)R * DM;
;       float sq = 0.f;
; #pragma unroll
;       for (int ni = 0; ni < 4; ++ni) {
;         const int c = nt * 128 + wn * 64 + ni * 16 + quad * 4;
;         const f32x4 xv = *(const f32x4*)(xr + c);
;         const f32x4 x1 = xv + acc[mi][ni];
;         *(f32x4*)(p.out + (size_t)R * DM + c) = x1;
;         const f32x4 gv = *(const f32x4*)(g2 + c);
;         u32x2 o; o[0] = pk2(x1[0] * gv[0], x1[1] * gv[1]); o[1] = pk2(x1[2] * gv[2], x1[3] * gv[3]);
;         *(u32x2*)(xb + c) = o;
;         sq += x1[0] * x1[0] + x1[1] * x1[1] + x1[2] * x1[2] + x1[3] * x1[3];
;       }
;       sq += __shfl_xor(sq, 16); sq += __shfl_xor(sq, 32);
;       if (quad == 0) atomicAdd(p.ss2 + R, sq);
;     }
.LBB0_806:
	v_lshlrev_b64 v[54:55], 12, v[54:55]
	v_lshl_add_u64 v[52:53], v[52:53], 0, v[54:55]
	v_lshl_add_u64 v[58:59], v[52:53], 0, v[72:73]
	v_readlane_b32 s68, v251, 49
	v_lshlrev_b64 v[60:61], 12, v[50:51]
	v_readlane_b32 s70, v251, 51
	v_readlane_b32 s71, v251, 52
	v_lshlrev_b64 v[62:63], 11, v[50:51]
	v_lshl_add_u64 v[62:63], s[52:53], 0, v[62:63]
	v_lshl_add_u64 v[60:61], s[70:71], 0, v[60:61]
	v_lshl_add_u64 v[60:61], v[60:61], 0, v[72:73]
	v_lshl_add_u64 v[62:63], v[70:71], 1, v[62:63]
	v_readlane_b32 s69, v251, 50
	v_readlane_b32 s72, v251, 53
	v_readlane_b32 s73, v251, 54
	v_readlane_b32 s74, v251, 55
	v_readlane_b32 s75, v251, 56
	v_readlane_b32 s76, v251, 57
	v_readlane_b32 s77, v251, 58
	v_readlane_b32 s78, v251, 59
	v_readlane_b32 s79, v251, 60
	v_readlane_b32 s80, v251, 61
	v_readlane_b32 s81, v251, 62
	v_readlane_b32 s82, v251, 63
	v_readlane_b32 s83, v252, 0
	global_load_dwordx4 v[112:115], v[58:59], off
	global_load_dwordx4 v[116:119], v[66:67], off
	global_load_dwordx4 v[120:123], v[58:59], off offset:64
	global_load_dwordx4 v[214:217], v[66:67], off offset:64
	global_load_dwordx4 v[222:225], v[58:59], off offset:128
	global_load_dwordx4 v[226:229], v[66:67], off offset:128
	global_load_dwordx4 v[74:77], v[58:59], off offset:192
	global_load_dwordx4 v[78:81], v[66:67], off offset:192
	s_waitcnt vmcnt(0)
	v_pk_add_f32 v[48:49], v[48:49], v[114:115]
	v_pk_add_f32 v[46:47], v[46:47], v[112:113]
	global_store_dwordx4 v[60:61], v[46:49], off
	v_mul_f32_e32 v0, v47, v47
	v_fmac_f32_e32 v0, v46, v46
	v_fmac_f32_e32 v0, v48, v48
	v_fmac_f32_e32 v0, v49, v49
	v_pk_mul_f32 v[54:55], v[48:49], v[118:119]
	v_pk_mul_f32 v[52:53], v[46:47], v[116:117]
	s_nop 0
	v_cvt_pk_bf16_f32 v52, v52, v53
	v_cvt_pk_bf16_f32 v53, v54, v55
	global_store_dwordx2 v[62:63], v[52:53], off
	v_pk_add_f32 v[44:45], v[44:45], v[122:123]
	v_pk_add_f32 v[42:43], v[42:43], v[120:121]
	global_store_dwordx4 v[60:61], v[42:45], off offset:64
	v_pk_mul_f32 v[54:55], v[44:45], v[216:217]
	v_pk_mul_f32 v[52:53], v[42:43], v[214:215]
	s_nop 0
	v_cvt_pk_bf16_f32 v52, v52, v53
	v_cvt_pk_bf16_f32 v53, v54, v55
	global_store_dwordx2 v[62:63], v[52:53], off offset:32
	v_pk_add_f32 v[40:41], v[40:41], v[224:225]
	v_pk_add_f32 v[38:39], v[38:39], v[222:223]
	global_store_dwordx4 v[60:61], v[38:41], off offset:128
	v_pk_mul_f32 v[54:55], v[40:41], v[228:229]
	v_pk_mul_f32 v[52:53], v[38:39], v[226:227]
	s_nop 0
	v_cvt_pk_bf16_f32 v52, v52, v53
	v_cvt_pk_bf16_f32 v53, v54, v55
	global_store_dwordx2 v[62:63], v[52:53], off offset:64
	v_pk_add_f32 v[54:55], v[36:37], v[76:77]
	v_pk_add_f32 v[52:53], v[34:35], v[74:75]
	global_store_dwordx4 v[60:61], v[52:55], off offset:192
	v_mul_f32_e32 v34, v43, v43
	v_fmac_f32_e32 v34, v42, v42
	v_fmac_f32_e32 v34, v44, v44
	v_fmac_f32_e32 v34, v45, v45
	v_add_f32_e32 v0, v0, v34
	v_mul_f32_e32 v34, v39, v39
	v_fmac_f32_e32 v34, v38, v38
	v_fmac_f32_e32 v34, v40, v40
	v_fmac_f32_e32 v34, v41, v41
	v_add_f32_e32 v0, v0, v34
	v_mul_f32_e32 v34, v53, v53
	v_fmac_f32_e32 v34, v52, v52
	v_fmac_f32_e32 v34, v54, v54
	v_fmac_f32_e32 v34, v55, v55
	v_add_f32_e32 v0, v0, v34
	ds_bpermute_b32 v34, v56, v0
	s_waitcnt lgkmcnt(0)
	v_add_f32_e32 v0, v0, v34
	ds_bpermute_b32 v34, v57, v0
	v_pk_mul_f32 v[36:37], v[54:55], v[80:81]
	v_pk_mul_f32 v[38:39], v[52:53], v[78:79]
	s_nop 0
	v_cvt_pk_bf16_f32 v38, v38, v39
	v_cvt_pk_bf16_f32 v39, v36, v37
	global_store_dwordx2 v[62:63], v[38:39], off offset:96
	s_and_saveexec_b64 s[24:25], s[0:1]
	s_cbranch_execz .LBB0_808
	v_readlane_b32 s68, v254, 52
	v_readlane_b32 s70, v254, 54
	v_readlane_b32 s71, v254, 55
	s_waitcnt lgkmcnt(0)
	v_add_f32_e32 v0, v0, v34
	v_readlane_b32 s69, v254, 53
	v_lshl_add_u64 v[36:37], v[50:51], 2, s[70:71]
	global_atomic_add_f32 v[36:37], v0, off
	v_readlane_b32 s72, v254, 56
	v_readlane_b32 s73, v254, 57
	v_readlane_b32 s74, v254, 58
	v_readlane_b32 s75, v254, 59

; DI unsigned pk2(float a, float b) { f32x2 v = {a, b}; bfv2 r = __builtin_convertvector(v, bfv2); return __builtin_bit_cast(unsigned, r); }
; DI void phase_out(const Params& p, int l, char* lds) {
;     ...
;     for (int mi = 0; mi < 4; ++mi) {
;       const int R = mt * 128 + wm * 64 + mi * 16 + l15;
;       const float* xr = x_row(p, l, R);
;       const float* g2 = p.ple_norm_g + l * DM;
;       bf16_t* xb = p.o_r + (size_t)R * DM;
;       float sq = 0.f;
; #pragma unroll
;       for (int ni = 0; ni < 4; ++ni) {
;         const int c = nt * 128 + wn * 64 + ni * 16 + quad * 4;
;         const f32x4 xv = *(const f32x4*)(xr + c);
;         const f32x4 x1 = xv + acc[mi][ni];
;         *(f32x4*)(p.out + (size_t)R * DM + c) = x1;
;         const f32x4 gv = *(const f32x4*)(g2 + c);
;         u32x2 o; o[0] = pk2(x1[0] * gv[0], x1[1] * gv[1]); o[1] = pk2(x1[2] * gv[2], x1[3] * gv[3]);
;         *(u32x2*)(xb + c) = o;
;         sq += x1[0] * x1[0] + x1[1] * x1[1] + x1[2] * x1[2] + x1[3] * x1[3];
;       }
;       sq += __shfl_xor(sq, 16); sq += __shfl_xor(sq, 32);
;       if (quad == 0) atomicAdd(p.ss2 + R, sq);
;     }
.LBB0_817:
	v_lshlrev_b64 v[38:39], 12, v[38:39]
	v_lshl_add_u64 v[36:37], v[36:37], 0, v[38:39]
	v_lshl_add_u64 v[40:41], v[36:37], 0, v[72:73]
	v_readlane_b32 s68, v251, 49
	v_lshlrev_b64 v[42:43], 12, v[34:35]
	v_readlane_b32 s70, v251, 51
	v_readlane_b32 s71, v251, 52
	v_lshlrev_b64 v[44:45], 11, v[34:35]
	v_lshl_add_u64 v[44:45], s[52:53], 0, v[44:45]
	v_lshl_add_u64 v[42:43], s[70:71], 0, v[42:43]
	v_lshl_add_u64 v[42:43], v[42:43], 0, v[72:73]
	v_lshl_add_u64 v[44:45], v[70:71], 1, v[44:45]
	v_readlane_b32 s69, v251, 50
	v_readlane_b32 s72, v251, 53
	v_readlane_b32 s73, v251, 54
	v_readlane_b32 s74, v251, 55
	v_readlane_b32 s75, v251, 56
	v_readlane_b32 s76, v251, 57
	v_readlane_b32 s77, v251, 58
	v_readlane_b32 s78, v251, 59
	v_readlane_b32 s79, v251, 60
	v_readlane_b32 s80, v251, 61
	v_readlane_b32 s81, v251, 62
	v_readlane_b32 s82, v251, 63
	v_readlane_b32 s83, v252, 0
	global_load_dwordx4 v[112:115], v[40:41], off
	global_load_dwordx4 v[116:119], v[66:67], off
	global_load_dwordx4 v[120:123], v[40:41], off offset:64
	global_load_dwordx4 v[214:217], v[66:67], off offset:64
	global_load_dwordx4 v[222:225], v[40:41], off offset:128
	global_load_dwordx4 v[226:229], v[66:67], off offset:128
	global_load_dwordx4 v[74:77], v[40:41], off offset:192
	global_load_dwordx4 v[78:81], v[66:67], off offset:192
	s_waitcnt vmcnt(0)
	v_pk_add_f32 v[32:33], v[32:33], v[114:115]
	v_pk_add_f32 v[30:31], v[30:31], v[112:113]
	global_store_dwordx4 v[42:43], v[30:33], off
	v_mul_f32_e32 v0, v31, v31
	v_fmac_f32_e32 v0, v30, v30
	v_fmac_f32_e32 v0, v32, v32
	v_fmac_f32_e32 v0, v33, v33
	v_pk_mul_f32 v[38:39], v[32:33], v[118:119]
	v_pk_mul_f32 v[36:37], v[30:31], v[116:117]
	s_nop 0
	v_cvt_pk_bf16_f32 v36, v36, v37
	v_cvt_pk_bf16_f32 v37, v38, v39
	global_store_dwordx2 v[44:45], v[36:37], off
	v_pk_add_f32 v[28:29], v[28:29], v[122:123]
	v_pk_add_f32 v[26:27], v[26:27], v[120:121]
	global_store_dwordx4 v[42:43], v[26:29], off offset:64
	v_pk_mul_f32 v[38:39], v[28:29], v[216:217]
	v_pk_mul_f32 v[36:37], v[26:27], v[214:215]
	s_nop 0
	v_cvt_pk_bf16_f32 v36, v36, v37
	v_cvt_pk_bf16_f32 v37, v38, v39
	global_store_dwordx2 v[44:45], v[36:37], off offset:32
	v_pk_add_f32 v[24:25], v[24:25], v[224:225]
	v_pk_add_f32 v[22:23], v[22:23], v[222:223]
	global_store_dwordx4 v[42:43], v[22:25], off offset:128
	v_pk_mul_f32 v[38:39], v[24:25], v[228:229]
	v_pk_mul_f32 v[36:37], v[22:23], v[226:227]
	s_nop 0
	v_cvt_pk_bf16_f32 v36, v36, v37
	v_cvt_pk_bf16_f32 v37, v38, v39
	global_store_dwordx2 v[44:45], v[36:37], off offset:64
	v_pk_add_f32 v[38:39], v[20:21], v[76:77]
	v_pk_add_f32 v[36:37], v[18:19], v[74:75]
	global_store_dwordx4 v[42:43], v[36:39], off offset:192
	v_mul_f32_e32 v18, v27, v27
	v_fmac_f32_e32 v18, v26, v26
	v_fmac_f32_e32 v18, v28, v28
	v_fmac_f32_e32 v18, v29, v29
	v_add_f32_e32 v0, v0, v18
	v_mul_f32_e32 v18, v23, v23
	v_fmac_f32_e32 v18, v22, v22
	v_fmac_f32_e32 v18, v24, v24
	v_fmac_f32_e32 v18, v25, v25
	v_add_f32_e32 v0, v0, v18
	v_mul_f32_e32 v18, v37, v37
	v_fmac_f32_e32 v18, v36, v36
	v_fmac_f32_e32 v18, v38, v38
	v_fmac_f32_e32 v18, v39, v39
	v_add_f32_e32 v0, v0, v18
	ds_bpermute_b32 v18, v56, v0
	s_waitcnt lgkmcnt(0)
	v_add_f32_e32 v0, v0, v18
	ds_bpermute_b32 v18, v57, v0
	v_pk_mul_f32 v[20:21], v[38:39], v[80:81]
	v_pk_mul_f32 v[22:23], v[36:37], v[78:79]
	s_nop 0
	v_cvt_pk_bf16_f32 v22, v22, v23
	v_cvt_pk_bf16_f32 v23, v20, v21
	global_store_dwordx2 v[44:45], v[22:23], off offset:96
	s_and_saveexec_b64 s[24:25], s[0:1]
	s_cbranch_execz .LBB0_819
	v_readlane_b32 s68, v254, 52
	v_readlane_b32 s70, v254, 54
	v_readlane_b32 s71, v254, 55
	s_waitcnt lgkmcnt(0)
	v_add_f32_e32 v0, v0, v18
	v_readlane_b32 s69, v254, 53
	v_lshl_add_u64 v[20:21], v[34:35], 2, s[70:71]
	global_atomic_add_f32 v[20:21], v0, off
	v_readlane_b32 s72, v254, 56
	v_readlane_b32 s73, v254, 57
	v_readlane_b32 s74, v254, 58
	v_readlane_b32 s75, v254, 59

; DI unsigned pk2(float a, float b) { f32x2 v = {a, b}; bfv2 r = __builtin_convertvector(v, bfv2); return __builtin_bit_cast(unsigned, r); }
; DI void phase_out(const Params& p, int l, char* lds) {
;     ...
;     for (int mi = 0; mi < 4; ++mi) {
;       const int R = mt * 128 + wm * 64 + mi * 16 + l15;
;       const float* xr = x_row(p, l, R);
;       const float* g2 = p.ple_norm_g + l * DM;
;       bf16_t* xb = p.o_r + (size_t)R * DM;
;       float sq = 0.f;
; #pragma unroll
;       for (int ni = 0; ni < 4; ++ni) {
;         const int c = nt * 128 + wn * 64 + ni * 16 + quad * 4;
;         const f32x4 xv = *(const f32x4*)(xr + c);
;         const f32x4 x1 = xv + acc[mi][ni];
;         *(f32x4*)(p.out + (size_t)R * DM + c) = x1;
;         const f32x4 gv = *(const f32x4*)(g2 + c);
;         u32x2 o; o[0] = pk2(x1[0] * gv[0], x1[1] * gv[1]); o[1] = pk2(x1[2] * gv[2], x1[3] * gv[3]);
;         *(u32x2*)(xb + c) = o;
;         sq += x1[0] * x1[0] + x1[1] * x1[1] + x1[2] * x1[2] + x1[3] * x1[3];
;       }
;       sq += __shfl_xor(sq, 16); sq += __shfl_xor(sq, 32);
;       if (quad == 0) atomicAdd(p.ss2 + R, sq);
;     }
.LBB0_828:
	v_lshlrev_b64 v[22:23], 12, v[22:23]
	v_lshl_add_u64 v[20:21], v[20:21], 0, v[22:23]
	v_lshl_add_u64 v[24:25], v[20:21], 0, v[72:73]
	v_readlane_b32 s68, v251, 49
	v_lshlrev_b64 v[26:27], 12, v[18:19]
	v_readlane_b32 s70, v251, 51
	v_readlane_b32 s71, v251, 52
	v_lshlrev_b64 v[28:29], 11, v[18:19]
	v_lshl_add_u64 v[28:29], s[52:53], 0, v[28:29]
	v_lshl_add_u64 v[26:27], s[70:71], 0, v[26:27]
	v_lshl_add_u64 v[26:27], v[26:27], 0, v[72:73]
	v_lshl_add_u64 v[28:29], v[70:71], 1, v[28:29]
	v_readlane_b32 s69, v251, 50
	v_readlane_b32 s72, v251, 53
	v_readlane_b32 s73, v251, 54
	v_readlane_b32 s74, v251, 55
	v_readlane_b32 s75, v251, 56
	v_readlane_b32 s76, v251, 57
	v_readlane_b32 s77, v251, 58
	v_readlane_b32 s78, v251, 59
	v_readlane_b32 s79, v251, 60
	v_readlane_b32 s80, v251, 61
	v_readlane_b32 s81, v251, 62
	v_readlane_b32 s82, v251, 63
	v_readlane_b32 s83, v252, 0
	global_load_dwordx4 v[112:115], v[24:25], off
	global_load_dwordx4 v[116:119], v[66:67], off
	global_load_dwordx4 v[120:123], v[24:25], off offset:64
	global_load_dwordx4 v[214:217], v[66:67], off offset:64
	global_load_dwordx4 v[222:225], v[24:25], off offset:128
	global_load_dwordx4 v[226:229], v[66:67], off offset:128
	global_load_dwordx4 v[74:77], v[24:25], off offset:192
	global_load_dwordx4 v[78:81], v[66:67], off offset:192
	s_waitcnt vmcnt(0)
	v_pk_add_f32 v[16:17], v[16:17], v[114:115]
	v_pk_add_f32 v[14:15], v[14:15], v[112:113]
	global_store_dwordx4 v[26:27], v[14:17], off
	v_mul_f32_e32 v0, v15, v15
	v_fmac_f32_e32 v0, v14, v14
	v_fmac_f32_e32 v0, v16, v16
	v_fmac_f32_e32 v0, v17, v17
	v_pk_mul_f32 v[22:23], v[16:17], v[118:119]
	v_pk_mul_f32 v[20:21], v[14:15], v[116:117]
	s_nop 0
	v_cvt_pk_bf16_f32 v20, v20, v21
	v_cvt_pk_bf16_f32 v21, v22, v23
	global_store_dwordx2 v[28:29], v[20:21], off
	v_pk_add_f32 v[12:13], v[12:13], v[122:123]
	v_pk_add_f32 v[10:11], v[10:11], v[120:121]
	global_store_dwordx4 v[26:27], v[10:13], off offset:64
	v_pk_mul_f32 v[22:23], v[12:13], v[216:217]
	v_pk_mul_f32 v[20:21], v[10:11], v[214:215]
	s_nop 0
	v_cvt_pk_bf16_f32 v20, v20, v21
	v_cvt_pk_bf16_f32 v21, v22, v23
	global_store_dwordx2 v[28:29], v[20:21], off offset:32
	v_pk_add_f32 v[8:9], v[8:9], v[224:225]
	v_pk_add_f32 v[6:7], v[6:7], v[222:223]
	global_store_dwordx4 v[26:27], v[6:9], off offset:128
	v_pk_mul_f32 v[22:23], v[8:9], v[228:229]
	v_pk_mul_f32 v[20:21], v[6:7], v[226:227]
	s_nop 0
	v_cvt_pk_bf16_f32 v20, v20, v21
	v_cvt_pk_bf16_f32 v21, v22, v23
	global_store_dwordx2 v[28:29], v[20:21], off offset:64
	v_pk_add_f32 v[22:23], v[4:5], v[76:77]
	v_pk_add_f32 v[20:21], v[2:3], v[74:75]
	global_store_dwordx4 v[26:27], v[20:23], off offset:192
	v_mul_f32_e32 v2, v11, v11
	v_fmac_f32_e32 v2, v10, v10
	v_fmac_f32_e32 v2, v12, v12
	v_fmac_f32_e32 v2, v13, v13
	v_add_f32_e32 v0, v0, v2
	v_mul_f32_e32 v2, v7, v7
	v_fmac_f32_e32 v2, v6, v6
	v_fmac_f32_e32 v2, v8, v8
	v_fmac_f32_e32 v2, v9, v9
	v_add_f32_e32 v0, v0, v2
	v_mul_f32_e32 v2, v21, v21
	v_fmac_f32_e32 v2, v20, v20
	v_fmac_f32_e32 v2, v22, v22
	v_fmac_f32_e32 v2, v23, v23
	v_add_f32_e32 v0, v0, v2
	ds_bpermute_b32 v2, v56, v0
	s_waitcnt lgkmcnt(0)
	v_add_f32_e32 v0, v0, v2
	ds_bpermute_b32 v2, v57, v0
	v_pk_mul_f32 v[4:5], v[22:23], v[80:81]
	v_pk_mul_f32 v[6:7], v[20:21], v[78:79]
	s_nop 0
	v_cvt_pk_bf16_f32 v6, v6, v7
	v_cvt_pk_bf16_f32 v7, v4, v5
	global_store_dwordx2 v[28:29], v[6:7], off offset:96
	s_and_saveexec_b64 s[24:25], s[0:1]
	s_cbranch_execz .LBB0_783
	v_readlane_b32 s40, v254, 52
	v_readlane_b32 s42, v254, 54
	v_readlane_b32 s43, v254, 55
	s_waitcnt lgkmcnt(0)
	v_add_f32_e32 v0, v0, v2
	v_readlane_b32 s41, v254, 53
	v_lshl_add_u64 v[4:5], v[18:19], 2, s[42:43]
	global_atomic_add_f32 v[4:5], v0, off
	v_readlane_b32 s44, v254, 56
	v_readlane_b32 s45, v254, 57
	v_readlane_b32 s46, v254, 58
	v_readlane_b32 s47, v254, 59
	s_branch .LBB0_783
